# OutB and Final GEMM epilogues: operand loads issued in batches of 12 into dead fragment registers, counted waits (on top of OutA hoist)
# speedup vs baseline: 1.0131x; 1.0131x over previous
.LBB0_654:
	v_lshl_add_u32 v144, s40, 8, v146
	v_lshl_or_b32 v142, s39, 8, v148
	v_ashrrev_i32_e32 v145, 31, v144
	v_ashrrev_i32_e32 v143, 31, v142
	v_lshlrev_b64 v[140:141], 10, v[144:145]
	v_lshl_add_u64 v[140:141], v[140:141], 0, v[142:143]
	v_lshlrev_b64 v[140:141], 1, v[140:141]
	v_lshl_add_u64 v[154:155], s[10:11], 0, v[140:141]
	s_mov_b32 s98, s10
	s_mov_b32 s99, s11
	global_load_dwordx4 v[178:181], v140, s[98:99]
	s_mov_b32 s98, s8
	s_mov_b32 s99, s9
	global_load_dwordx4 v[182:185], v140, s[98:99]
	s_mov_b32 s98, s10
	s_mov_b32 s99, s11
	global_load_dwordx4 v[186:189], v140, s[98:99] offset:256
	s_mov_b32 s98, s8
	s_mov_b32 s99, s9
	global_load_dwordx4 v[190:193], v140, s[98:99] offset:256
	s_add_u32 s98, s10, 0x8000
	s_addc_u32 s99, s11, 0
	global_load_dwordx4 v[208:211], v140, s[98:99]
	s_add_u32 s98, s8, 0x8000
	s_addc_u32 s99, s9, 0
	global_load_dwordx4 v[212:215], v140, s[98:99]
	s_add_u32 s98, s10, 0x8000
	s_addc_u32 s99, s11, 0
	global_load_dwordx4 v[216:219], v140, s[98:99] offset:256
	s_add_u32 s98, s8, 0x8000
	s_addc_u32 s99, s9, 0
	global_load_dwordx4 v[220:223], v140, s[98:99] offset:256
	s_add_u32 s98, s10, 0x10000
	s_addc_u32 s99, s11, 0
	global_load_dwordx4 v[224:227], v140, s[98:99]
	s_add_u32 s98, s8, 0x10000
	s_addc_u32 s99, s9, 0
	global_load_dwordx4 v[228:231], v140, s[98:99]
	s_add_u32 s98, s10, 0x10000
	s_addc_u32 s99, s11, 0
	global_load_dwordx4 v[236:239], v140, s[98:99] offset:256
	s_add_u32 s98, s8, 0x10000
	s_addc_u32 s99, s9, 0
	global_load_dwordx4 v[240:243], v140, s[98:99] offset:256
	v_lshl_add_u64 v[164:165], s[8:9], 0, v[140:141]
	s_mov_b64 s[2:3], 0x40000
	s_andn2_b64 vcc, exec, s[6:7]
	s_waitcnt vmcnt(10)
	v_lshlrev_b32_e32 v156, 16, v178
	v_and_b32_e32 v157, 0xffff0000, v178
	v_lshlrev_b32_e32 v158, 16, v179
	v_and_b32_e32 v159, 0xffff0000, v179
	v_lshlrev_b32_e32 v160, 16, v180
	v_and_b32_e32 v161, 0xffff0000, v180
	v_lshlrev_b32_e32 v162, 16, v181
	v_and_b32_e32 v163, 0xffff0000, v181
	s_waitcnt vmcnt(10)
	v_lshlrev_b32_e32 v166, 16, v182
	v_and_b32_e32 v167, 0xffff0000, v182
	v_lshlrev_b32_e32 v150, 16, v183
	v_and_b32_e32 v151, 0xffff0000, v183
	v_lshlrev_b32_e32 v168, 16, v184
	v_and_b32_e32 v169, 0xffff0000, v184
	v_lshlrev_b32_e32 v152, 16, v185
	v_and_b32_e32 v153, 0xffff0000, v185
	v_pk_fma_f32 v[126:127], v[126:127], v[158:159], v[150:151]
	v_pk_fma_f32 v[124:125], v[124:125], v[156:157], v[166:167]
	v_pk_fma_f32 v[150:151], v[122:123], v[162:163], v[152:153]
	v_pk_fma_f32 v[122:123], v[120:121], v[160:161], v[168:169]
	v_cvt_pk_bf16_f32 v120, v124, v125
	v_cvt_pk_bf16_f32 v121, v126, v127
	v_cvt_pk_bf16_f32 v122, v122, v123
	v_cvt_pk_bf16_f32 v123, v150, v151
	global_store_dwordx4 v[164:165], v[120:123], off
	s_waitcnt vmcnt(9)
	v_lshlrev_b32_e32 v124, 16, v186
	v_and_b32_e32 v125, 0xffff0000, v186
	v_lshlrev_b32_e32 v126, 16, v187
	v_and_b32_e32 v127, 0xffff0000, v187
	v_lshlrev_b32_e32 v150, 16, v188
	v_and_b32_e32 v151, 0xffff0000, v188
	v_lshlrev_b32_e32 v152, 16, v189
	v_and_b32_e32 v153, 0xffff0000, v189
	s_waitcnt vmcnt(9)
	v_lshlrev_b32_e32 v154, 16, v190
	v_and_b32_e32 v155, 0xffff0000, v190
	v_lshlrev_b32_e32 v120, 16, v191
	v_and_b32_e32 v121, 0xffff0000, v191
	v_lshlrev_b32_e32 v156, 16, v192
	v_and_b32_e32 v157, 0xffff0000, v192
	v_lshlrev_b32_e32 v122, 16, v193
	v_and_b32_e32 v123, 0xffff0000, v193
	v_pk_fma_f32 v[118:119], v[118:119], v[126:127], v[120:121]
	v_pk_fma_f32 v[116:117], v[116:117], v[124:125], v[154:155]
	v_pk_fma_f32 v[120:121], v[114:115], v[152:153], v[122:123]
	v_pk_fma_f32 v[114:115], v[112:113], v[150:151], v[156:157]
	v_cvt_pk_bf16_f32 v112, v116, v117
	v_cvt_pk_bf16_f32 v113, v118, v119
	v_cvt_pk_bf16_f32 v114, v114, v115
	v_cvt_pk_bf16_f32 v115, v120, v121
	global_store_dwordx4 v[164:165], v[112:115], off offset:256
	s_nop 1
	s_nop 1
	v_or_b32_e32 v112, 16, v144
	v_ashrrev_i32_e32 v113, 31, v112
	v_lshlrev_b64 v[112:113], 10, v[112:113]
	v_lshl_add_u64 v[112:113], v[112:113], 0, v[142:143]
	v_lshlrev_b64 v[118:119], 1, v[112:113]
	v_lshl_add_u64 v[112:113], s[10:11], 0, v[118:119]
	v_lshl_add_u64 v[118:119], s[8:9], 0, v[118:119]
	s_waitcnt vmcnt(8)
	v_lshlrev_b32_e32 v120, 16, v208
	v_and_b32_e32 v121, 0xffff0000, v208
	v_lshlrev_b32_e32 v122, 16, v209
	v_and_b32_e32 v123, 0xffff0000, v209
	v_lshlrev_b32_e32 v124, 16, v210
	v_and_b32_e32 v125, 0xffff0000, v210
	v_lshlrev_b32_e32 v126, 16, v211
	v_and_b32_e32 v127, 0xffff0000, v211
	s_waitcnt vmcnt(8)
	v_lshlrev_b32_e32 v150, 16, v212
	v_and_b32_e32 v151, 0xffff0000, v212
	v_lshlrev_b32_e32 v114, 16, v213
	v_and_b32_e32 v115, 0xffff0000, v213
	v_lshlrev_b32_e32 v152, 16, v214
	v_and_b32_e32 v153, 0xffff0000, v214
	v_lshlrev_b32_e32 v116, 16, v215
	v_and_b32_e32 v117, 0xffff0000, v215
	v_pk_fma_f32 v[110:111], v[110:111], v[122:123], v[114:115]
	v_pk_fma_f32 v[108:109], v[108:109], v[120:121], v[150:151]
	v_pk_fma_f32 v[114:115], v[106:107], v[126:127], v[116:117]
	v_pk_fma_f32 v[106:107], v[104:105], v[124:125], v[152:153]
	v_cvt_pk_bf16_f32 v104, v108, v109
	v_cvt_pk_bf16_f32 v105, v110, v111
	v_cvt_pk_bf16_f32 v106, v106, v107
	v_cvt_pk_bf16_f32 v107, v114, v115
	global_store_dwordx4 v[118:119], v[104:107], off
	s_waitcnt vmcnt(7)
	v_lshlrev_b32_e32 v108, 16, v216
	v_and_b32_e32 v109, 0xffff0000, v216
	v_lshlrev_b32_e32 v110, 16, v217
	v_and_b32_e32 v111, 0xffff0000, v217
	v_lshlrev_b32_e32 v112, 16, v218
	v_and_b32_e32 v113, 0xffff0000, v218
	v_lshlrev_b32_e32 v114, 16, v219
	v_and_b32_e32 v115, 0xffff0000, v219
	s_waitcnt vmcnt(7)
	v_lshlrev_b32_e32 v116, 16, v220
	v_and_b32_e32 v117, 0xffff0000, v220
	v_lshlrev_b32_e32 v104, 16, v221
	v_and_b32_e32 v105, 0xffff0000, v221
	v_lshlrev_b32_e32 v120, 16, v222
	v_and_b32_e32 v121, 0xffff0000, v222
	v_lshlrev_b32_e32 v106, 16, v223
	v_and_b32_e32 v107, 0xffff0000, v223
	v_pk_fma_f32 v[102:103], v[102:103], v[110:111], v[104:105]
	v_pk_fma_f32 v[100:101], v[100:101], v[108:109], v[116:117]
	v_pk_fma_f32 v[104:105], v[98:99], v[114:115], v[106:107]
	v_pk_fma_f32 v[98:99], v[96:97], v[112:113], v[120:121]
	v_cvt_pk_bf16_f32 v96, v100, v101
	v_cvt_pk_bf16_f32 v97, v102, v103
	v_cvt_pk_bf16_f32 v98, v98, v99
	v_cvt_pk_bf16_f32 v99, v104, v105
	global_store_dwordx4 v[118:119], v[96:99], off offset:256
	s_nop 1
	s_nop 1
	v_or_b32_e32 v96, 32, v144
	v_ashrrev_i32_e32 v97, 31, v96
	v_lshlrev_b64 v[96:97], 10, v[96:97]
	v_lshl_add_u64 v[96:97], v[96:97], 0, v[142:143]
	v_lshlrev_b64 v[102:103], 1, v[96:97]
	v_lshl_add_u64 v[96:97], s[10:11], 0, v[102:103]
	v_lshl_add_u64 v[102:103], s[8:9], 0, v[102:103]
	s_waitcnt vmcnt(6)
	v_lshlrev_b32_e32 v104, 16, v224
	v_and_b32_e32 v105, 0xffff0000, v224
	v_lshlrev_b32_e32 v106, 16, v225
	v_and_b32_e32 v107, 0xffff0000, v225
	v_lshlrev_b32_e32 v108, 16, v226
	v_and_b32_e32 v109, 0xffff0000, v226
	v_lshlrev_b32_e32 v110, 16, v227
	v_and_b32_e32 v111, 0xffff0000, v227
	s_waitcnt vmcnt(6)
	v_lshlrev_b32_e32 v112, 16, v228
	v_and_b32_e32 v113, 0xffff0000, v228
	v_lshlrev_b32_e32 v98, 16, v229
	v_and_b32_e32 v99, 0xffff0000, v229
	v_lshlrev_b32_e32 v114, 16, v230
	v_and_b32_e32 v115, 0xffff0000, v230
	v_lshlrev_b32_e32 v100, 16, v231
	v_and_b32_e32 v101, 0xffff0000, v231
	v_pk_fma_f32 v[94:95], v[94:95], v[106:107], v[98:99]
	v_pk_fma_f32 v[92:93], v[92:93], v[104:105], v[112:113]
	v_pk_fma_f32 v[98:99], v[90:91], v[110:111], v[100:101]
	v_pk_fma_f32 v[90:91], v[88:89], v[108:109], v[114:115]
	v_cvt_pk_bf16_f32 v88, v92, v93
	v_cvt_pk_bf16_f32 v89, v94, v95
	v_cvt_pk_bf16_f32 v90, v90, v91
	v_cvt_pk_bf16_f32 v91, v98, v99
	global_store_dwordx4 v[102:103], v[88:91], off
	s_waitcnt vmcnt(5)
	v_lshlrev_b32_e32 v92, 16, v236
	v_and_b32_e32 v93, 0xffff0000, v236
	v_lshlrev_b32_e32 v94, 16, v237
	v_and_b32_e32 v95, 0xffff0000, v237
	v_lshlrev_b32_e32 v96, 16, v238
	v_and_b32_e32 v97, 0xffff0000, v238
	v_lshlrev_b32_e32 v98, 16, v239
	v_and_b32_e32 v99, 0xffff0000, v239
	s_waitcnt vmcnt(5)
	v_lshlrev_b32_e32 v100, 16, v240
	v_and_b32_e32 v101, 0xffff0000, v240
	v_lshlrev_b32_e32 v88, 16, v241
	v_and_b32_e32 v89, 0xffff0000, v241
	v_lshlrev_b32_e32 v104, 16, v242
	v_and_b32_e32 v105, 0xffff0000, v242
	v_lshlrev_b32_e32 v90, 16, v243
	v_and_b32_e32 v91, 0xffff0000, v243
	v_pk_fma_f32 v[86:87], v[86:87], v[94:95], v[88:89]
	v_pk_fma_f32 v[84:85], v[84:85], v[92:93], v[100:101]
	v_pk_fma_f32 v[88:89], v[82:83], v[98:99], v[90:91]
	v_pk_fma_f32 v[82:83], v[80:81], v[96:97], v[104:105]
	v_cvt_pk_bf16_f32 v80, v84, v85
	v_cvt_pk_bf16_f32 v81, v86, v87
	v_cvt_pk_bf16_f32 v82, v82, v83
	v_cvt_pk_bf16_f32 v83, v88, v89
	global_store_dwordx4 v[102:103], v[80:83], off offset:256
	s_nop 1
	s_nop 1
	v_or_b32_e32 v80, 48, v144
	v_ashrrev_i32_e32 v81, 31, v80
	v_lshlrev_b64 v[80:81], 10, v[80:81]
	v_lshl_add_u64 v[80:81], v[80:81], 0, v[142:143]
	v_lshlrev_b64 v[86:87], 1, v[80:81]
	v_lshl_add_u64 v[80:81], s[10:11], 0, v[86:87]
	s_add_u32 s98, s10, 0x18000
	s_addc_u32 s99, s11, 0
	global_load_dwordx4 v[178:181], v140, s[98:99]
	s_add_u32 s98, s8, 0x18000
	s_addc_u32 s99, s9, 0
	global_load_dwordx4 v[182:185], v140, s[98:99]
	s_add_u32 s98, s10, 0x18000
	s_addc_u32 s99, s11, 0
	global_load_dwordx4 v[186:189], v140, s[98:99] offset:256
	s_add_u32 s98, s8, 0x18000
	s_addc_u32 s99, s9, 0
	global_load_dwordx4 v[190:193], v140, s[98:99] offset:256
	s_add_u32 s98, s10, 0x40000
	s_addc_u32 s99, s11, 0
	global_load_dwordx4 v[208:211], v140, s[98:99]
	s_add_u32 s98, s8, 0x40000
	s_addc_u32 s99, s9, 0
	global_load_dwordx4 v[212:215], v140, s[98:99]
	s_add_u32 s98, s10, 0x40000
	s_addc_u32 s99, s11, 0
	global_load_dwordx4 v[216:219], v140, s[98:99] offset:256
	s_add_u32 s98, s8, 0x40000
	s_addc_u32 s99, s9, 0
	global_load_dwordx4 v[220:223], v140, s[98:99] offset:256
	s_add_u32 s98, s10, 0x48000
	s_addc_u32 s99, s11, 0
	global_load_dwordx4 v[224:227], v140, s[98:99]
	s_add_u32 s98, s8, 0x48000
	s_addc_u32 s99, s9, 0
	global_load_dwordx4 v[228:231], v140, s[98:99]
	s_add_u32 s98, s10, 0x48000
	s_addc_u32 s99, s11, 0
	global_load_dwordx4 v[236:239], v140, s[98:99] offset:256
	s_add_u32 s98, s8, 0x48000
	s_addc_u32 s99, s9, 0
	global_load_dwordx4 v[240:243], v140, s[98:99] offset:256
	v_lshl_add_u64 v[86:87], s[8:9], 0, v[86:87]
	s_waitcnt vmcnt(10)
	v_lshlrev_b32_e32 v88, 16, v178
	v_and_b32_e32 v89, 0xffff0000, v178
	v_lshlrev_b32_e32 v90, 16, v179
	v_and_b32_e32 v91, 0xffff0000, v179
	v_lshlrev_b32_e32 v92, 16, v180
	v_and_b32_e32 v93, 0xffff0000, v180
	v_lshlrev_b32_e32 v94, 16, v181
	v_and_b32_e32 v95, 0xffff0000, v181
	s_waitcnt vmcnt(10)
	v_lshlrev_b32_e32 v96, 16, v182
	v_and_b32_e32 v97, 0xffff0000, v182
	v_lshlrev_b32_e32 v82, 16, v183
	v_and_b32_e32 v83, 0xffff0000, v183
	v_lshlrev_b32_e32 v98, 16, v184
	v_and_b32_e32 v99, 0xffff0000, v184
	v_lshlrev_b32_e32 v84, 16, v185
	v_and_b32_e32 v85, 0xffff0000, v185
	v_pk_fma_f32 v[78:79], v[78:79], v[90:91], v[82:83]
	v_pk_fma_f32 v[76:77], v[76:77], v[88:89], v[96:97]
	v_pk_fma_f32 v[82:83], v[74:75], v[94:95], v[84:85]
	v_pk_fma_f32 v[74:75], v[72:73], v[92:93], v[98:99]
	v_cvt_pk_bf16_f32 v72, v76, v77
	v_cvt_pk_bf16_f32 v73, v78, v79
	v_cvt_pk_bf16_f32 v74, v74, v75
	v_cvt_pk_bf16_f32 v75, v82, v83
	global_store_dwordx4 v[86:87], v[72:75], off
	s_waitcnt vmcnt(9)
	v_lshlrev_b32_e32 v76, 16, v186
	v_and_b32_e32 v77, 0xffff0000, v186
	v_lshlrev_b32_e32 v78, 16, v187
	v_and_b32_e32 v79, 0xffff0000, v187
	v_lshlrev_b32_e32 v80, 16, v188
	v_and_b32_e32 v81, 0xffff0000, v188
	v_lshlrev_b32_e32 v82, 16, v189
	v_and_b32_e32 v83, 0xffff0000, v189
	s_waitcnt vmcnt(9)
	v_lshlrev_b32_e32 v84, 16, v190
	v_and_b32_e32 v85, 0xffff0000, v190
	v_lshlrev_b32_e32 v72, 16, v191
	v_and_b32_e32 v73, 0xffff0000, v191
	v_lshlrev_b32_e32 v88, 16, v192
	v_and_b32_e32 v89, 0xffff0000, v192
	v_lshlrev_b32_e32 v74, 16, v193
	v_and_b32_e32 v75, 0xffff0000, v193
	v_pk_fma_f32 v[70:71], v[70:71], v[78:79], v[72:73]
	v_pk_fma_f32 v[68:69], v[68:69], v[76:77], v[84:85]
	v_pk_fma_f32 v[72:73], v[66:67], v[82:83], v[74:75]
	v_pk_fma_f32 v[66:67], v[64:65], v[80:81], v[88:89]
	v_cvt_pk_bf16_f32 v64, v68, v69
	v_cvt_pk_bf16_f32 v65, v70, v71
	v_cvt_pk_bf16_f32 v66, v66, v67
	v_cvt_pk_bf16_f32 v67, v72, v73
	global_store_dwordx4 v[86:87], v[64:67], off offset:256
	v_lshl_add_u64 v[70:71], v[140:141], 0, s[2:3]
	s_mov_b64 s[2:3], 0x48000
	v_lshl_add_u64 v[64:65], s[10:11], 0, v[70:71]
	v_lshl_add_u64 v[70:71], s[8:9], 0, v[70:71]
	s_waitcnt vmcnt(8)
	v_lshlrev_b32_e32 v72, 16, v208
	v_and_b32_e32 v73, 0xffff0000, v208
	v_lshlrev_b32_e32 v74, 16, v209
	v_and_b32_e32 v75, 0xffff0000, v209
	v_lshlrev_b32_e32 v76, 16, v210
	v_and_b32_e32 v77, 0xffff0000, v210
	v_lshlrev_b32_e32 v78, 16, v211
	v_and_b32_e32 v79, 0xffff0000, v211
	s_waitcnt vmcnt(8)
	v_lshlrev_b32_e32 v80, 16, v212
	v_and_b32_e32 v81, 0xffff0000, v212
	v_lshlrev_b32_e32 v66, 16, v213
	v_and_b32_e32 v67, 0xffff0000, v213
	v_lshlrev_b32_e32 v82, 16, v214
	v_and_b32_e32 v83, 0xffff0000, v214
	v_lshlrev_b32_e32 v68, 16, v215
	v_and_b32_e32 v69, 0xffff0000, v215
	v_pk_fma_f32 v[62:63], v[62:63], v[74:75], v[66:67]
	v_pk_fma_f32 v[60:61], v[60:61], v[72:73], v[80:81]
	v_pk_fma_f32 v[66:67], v[58:59], v[78:79], v[68:69]
	v_pk_fma_f32 v[58:59], v[56:57], v[76:77], v[82:83]
	v_cvt_pk_bf16_f32 v56, v60, v61
	v_cvt_pk_bf16_f32 v57, v62, v63
	v_cvt_pk_bf16_f32 v58, v58, v59
	v_cvt_pk_bf16_f32 v59, v66, v67
	global_store_dwordx4 v[70:71], v[56:59], off
	s_waitcnt vmcnt(7)
	v_lshlrev_b32_e32 v60, 16, v216
	v_and_b32_e32 v61, 0xffff0000, v216
	v_lshlrev_b32_e32 v62, 16, v217
	v_and_b32_e32 v63, 0xffff0000, v217
	v_lshlrev_b32_e32 v64, 16, v218
	v_and_b32_e32 v65, 0xffff0000, v218
	v_lshlrev_b32_e32 v66, 16, v219
	v_and_b32_e32 v67, 0xffff0000, v219
	s_waitcnt vmcnt(7)
	v_lshlrev_b32_e32 v68, 16, v220
	v_and_b32_e32 v69, 0xffff0000, v220
	v_lshlrev_b32_e32 v56, 16, v221
	v_and_b32_e32 v57, 0xffff0000, v221
	v_lshlrev_b32_e32 v72, 16, v222
	v_and_b32_e32 v73, 0xffff0000, v222
	v_lshlrev_b32_e32 v58, 16, v223
	v_and_b32_e32 v59, 0xffff0000, v223
	v_pk_fma_f32 v[54:55], v[54:55], v[62:63], v[56:57]
	v_pk_fma_f32 v[52:53], v[52:53], v[60:61], v[68:69]
	v_pk_fma_f32 v[56:57], v[50:51], v[66:67], v[58:59]
	v_pk_fma_f32 v[50:51], v[48:49], v[64:65], v[72:73]
	v_cvt_pk_bf16_f32 v48, v52, v53
	v_cvt_pk_bf16_f32 v49, v54, v55
	v_cvt_pk_bf16_f32 v50, v50, v51
	v_cvt_pk_bf16_f32 v51, v56, v57
	global_store_dwordx4 v[70:71], v[48:51], off offset:256
	v_lshl_add_u64 v[54:55], v[140:141], 0, s[2:3]
	s_mov_b64 s[2:3], 0x50000
	v_lshl_add_u64 v[48:49], s[10:11], 0, v[54:55]
	v_lshl_add_u64 v[54:55], s[8:9], 0, v[54:55]
	s_waitcnt vmcnt(6)
	v_lshlrev_b32_e32 v56, 16, v224
	v_and_b32_e32 v57, 0xffff0000, v224
	v_lshlrev_b32_e32 v58, 16, v225
	v_and_b32_e32 v59, 0xffff0000, v225
	v_lshlrev_b32_e32 v60, 16, v226
	v_and_b32_e32 v61, 0xffff0000, v226
	v_lshlrev_b32_e32 v62, 16, v227
	v_and_b32_e32 v63, 0xffff0000, v227
	s_waitcnt vmcnt(6)
	v_lshlrev_b32_e32 v64, 16, v228
	v_and_b32_e32 v65, 0xffff0000, v228
	v_lshlrev_b32_e32 v50, 16, v229
	v_and_b32_e32 v51, 0xffff0000, v229
	v_lshlrev_b32_e32 v66, 16, v230
	v_and_b32_e32 v67, 0xffff0000, v230
	v_lshlrev_b32_e32 v52, 16, v231
	v_and_b32_e32 v53, 0xffff0000, v231
	v_pk_fma_f32 v[46:47], v[46:47], v[58:59], v[50:51]
	v_pk_fma_f32 v[44:45], v[44:45], v[56:57], v[64:65]
	v_pk_fma_f32 v[50:51], v[42:43], v[62:63], v[52:53]
	v_pk_fma_f32 v[42:43], v[40:41], v[60:61], v[66:67]
	v_cvt_pk_bf16_f32 v40, v44, v45
	v_cvt_pk_bf16_f32 v41, v46, v47
	v_cvt_pk_bf16_f32 v42, v42, v43
	v_cvt_pk_bf16_f32 v43, v50, v51
	global_store_dwordx4 v[54:55], v[40:43], off
	s_waitcnt vmcnt(5)
	v_lshlrev_b32_e32 v44, 16, v236
	v_and_b32_e32 v45, 0xffff0000, v236
	v_lshlrev_b32_e32 v46, 16, v237
	v_and_b32_e32 v47, 0xffff0000, v237
	v_lshlrev_b32_e32 v48, 16, v238
	v_and_b32_e32 v49, 0xffff0000, v238
	v_lshlrev_b32_e32 v50, 16, v239
	v_and_b32_e32 v51, 0xffff0000, v239
	s_waitcnt vmcnt(5)
	v_lshlrev_b32_e32 v52, 16, v240
	v_and_b32_e32 v53, 0xffff0000, v240
	v_lshlrev_b32_e32 v40, 16, v241
	v_and_b32_e32 v41, 0xffff0000, v241
	v_lshlrev_b32_e32 v56, 16, v242
	v_and_b32_e32 v57, 0xffff0000, v242
	v_lshlrev_b32_e32 v42, 16, v243
	v_and_b32_e32 v43, 0xffff0000, v243
	v_pk_fma_f32 v[38:39], v[38:39], v[46:47], v[40:41]
	v_pk_fma_f32 v[36:37], v[36:37], v[44:45], v[52:53]
	v_pk_fma_f32 v[40:41], v[34:35], v[50:51], v[42:43]
	v_pk_fma_f32 v[34:35], v[32:33], v[48:49], v[56:57]
	v_cvt_pk_bf16_f32 v32, v36, v37
	v_cvt_pk_bf16_f32 v33, v38, v39
	v_cvt_pk_bf16_f32 v34, v34, v35
	v_cvt_pk_bf16_f32 v35, v40, v41
	global_store_dwordx4 v[54:55], v[32:35], off offset:256
	v_lshl_add_u64 v[38:39], v[140:141], 0, s[2:3]
	s_mov_b64 s[2:3], 0x58000
	v_lshl_add_u64 v[32:33], s[10:11], 0, v[38:39]
	s_add_u32 s98, s10, 0x50000
	s_addc_u32 s99, s11, 0
	global_load_dwordx4 v[178:181], v140, s[98:99]
	s_add_u32 s98, s8, 0x50000
	s_addc_u32 s99, s9, 0
	global_load_dwordx4 v[182:185], v140, s[98:99]
	s_add_u32 s98, s10, 0x50000
	s_addc_u32 s99, s11, 0
	global_load_dwordx4 v[186:189], v140, s[98:99] offset:256
	s_add_u32 s98, s8, 0x50000
	s_addc_u32 s99, s9, 0
	global_load_dwordx4 v[190:193], v140, s[98:99] offset:256
	s_add_u32 s98, s10, 0x58000
	s_addc_u32 s99, s11, 0
	global_load_dwordx4 v[208:211], v140, s[98:99]
	s_add_u32 s98, s8, 0x58000
	s_addc_u32 s99, s9, 0
	global_load_dwordx4 v[212:215], v140, s[98:99]
	s_add_u32 s98, s10, 0x58000
	s_addc_u32 s99, s11, 0
	global_load_dwordx4 v[216:219], v140, s[98:99] offset:256
	s_add_u32 s98, s8, 0x58000
	s_addc_u32 s99, s9, 0
	global_load_dwordx4 v[220:223], v140, s[98:99] offset:256
	v_lshl_add_u64 v[38:39], s[8:9], 0, v[38:39]
	s_waitcnt vmcnt(6)
	v_lshlrev_b32_e32 v40, 16, v178
	v_and_b32_e32 v41, 0xffff0000, v178
	v_lshlrev_b32_e32 v42, 16, v179
	v_and_b32_e32 v43, 0xffff0000, v179
	v_lshlrev_b32_e32 v44, 16, v180
	v_and_b32_e32 v45, 0xffff0000, v180
	v_lshlrev_b32_e32 v46, 16, v181
	v_and_b32_e32 v47, 0xffff0000, v181
	s_waitcnt vmcnt(6)
	v_lshlrev_b32_e32 v48, 16, v182
	v_and_b32_e32 v49, 0xffff0000, v182
	v_lshlrev_b32_e32 v34, 16, v183
	v_and_b32_e32 v35, 0xffff0000, v183
	v_lshlrev_b32_e32 v50, 16, v184
	v_and_b32_e32 v51, 0xffff0000, v184
	v_lshlrev_b32_e32 v36, 16, v185
	v_and_b32_e32 v37, 0xffff0000, v185
	v_pk_fma_f32 v[30:31], v[30:31], v[42:43], v[34:35]
	v_pk_fma_f32 v[28:29], v[28:29], v[40:41], v[48:49]
	v_pk_fma_f32 v[34:35], v[26:27], v[46:47], v[36:37]
	v_pk_fma_f32 v[26:27], v[24:25], v[44:45], v[50:51]
	v_cvt_pk_bf16_f32 v24, v28, v29
	v_cvt_pk_bf16_f32 v25, v30, v31
	v_cvt_pk_bf16_f32 v26, v26, v27
	v_cvt_pk_bf16_f32 v27, v34, v35
	global_store_dwordx4 v[38:39], v[24:27], off
	s_waitcnt vmcnt(5)
	v_lshlrev_b32_e32 v28, 16, v186
	v_and_b32_e32 v29, 0xffff0000, v186
	v_lshlrev_b32_e32 v30, 16, v187
	v_and_b32_e32 v31, 0xffff0000, v187
	v_lshlrev_b32_e32 v32, 16, v188
	v_and_b32_e32 v33, 0xffff0000, v188
	v_lshlrev_b32_e32 v34, 16, v189
	v_and_b32_e32 v35, 0xffff0000, v189
	s_waitcnt vmcnt(5)
	v_lshlrev_b32_e32 v36, 16, v190
	v_and_b32_e32 v37, 0xffff0000, v190
	v_lshlrev_b32_e32 v24, 16, v191
	v_and_b32_e32 v25, 0xffff0000, v191
	v_lshlrev_b32_e32 v40, 16, v192
	v_and_b32_e32 v41, 0xffff0000, v192
	v_lshlrev_b32_e32 v26, 16, v193
	v_and_b32_e32 v27, 0xffff0000, v193
	v_pk_fma_f32 v[22:23], v[22:23], v[30:31], v[24:25]
	v_pk_fma_f32 v[20:21], v[20:21], v[28:29], v[36:37]
	v_pk_fma_f32 v[24:25], v[18:19], v[34:35], v[26:27]
	v_pk_fma_f32 v[18:19], v[16:17], v[32:33], v[40:41]
	v_cvt_pk_bf16_f32 v16, v20, v21
	v_cvt_pk_bf16_f32 v17, v22, v23
	v_cvt_pk_bf16_f32 v18, v18, v19
	v_cvt_pk_bf16_f32 v19, v24, v25
	global_store_dwordx4 v[38:39], v[16:19], off offset:256
	v_lshl_add_u64 v[22:23], v[140:141], 0, s[2:3]
	s_mov_b64 s[2:3], -1
	v_lshl_add_u64 v[16:17], s[10:11], 0, v[22:23]
	s_waitcnt vmcnt(4)
	v_lshlrev_b32_e32 v24, 16, v208
	v_and_b32_e32 v25, 0xffff0000, v208
	v_lshlrev_b32_e32 v26, 16, v209
	v_and_b32_e32 v27, 0xffff0000, v209
	v_lshl_add_u64 v[18:19], s[8:9], 0, v[22:23]
	v_lshlrev_b32_e32 v28, 16, v210
	v_and_b32_e32 v29, 0xffff0000, v210
	v_lshlrev_b32_e32 v30, 16, v211
	v_and_b32_e32 v31, 0xffff0000, v211
	s_waitcnt vmcnt(4)
	v_lshlrev_b32_e32 v32, 16, v212
	v_and_b32_e32 v33, 0xffff0000, v212
	v_lshlrev_b32_e32 v20, 16, v213
	v_and_b32_e32 v21, 0xffff0000, v213
	v_lshlrev_b32_e32 v34, 16, v214
	v_and_b32_e32 v35, 0xffff0000, v214
	v_lshlrev_b32_e32 v22, 16, v215
	v_and_b32_e32 v23, 0xffff0000, v215
	v_pk_fma_f32 v[14:15], v[14:15], v[26:27], v[20:21]
	v_pk_fma_f32 v[12:13], v[12:13], v[24:25], v[32:33]
	v_pk_fma_f32 v[20:21], v[10:11], v[30:31], v[22:23]
	v_pk_fma_f32 v[10:11], v[8:9], v[28:29], v[34:35]
	v_cvt_pk_bf16_f32 v8, v12, v13
	v_cvt_pk_bf16_f32 v9, v14, v15
	v_cvt_pk_bf16_f32 v10, v10, v11
	v_cvt_pk_bf16_f32 v11, v20, v21
	global_store_dwordx4 v[18:19], v[8:11], off
	s_waitcnt vmcnt(3)
	v_lshlrev_b32_e32 v12, 16, v216
	v_and_b32_e32 v13, 0xffff0000, v216
	v_lshlrev_b32_e32 v14, 16, v217
	v_and_b32_e32 v15, 0xffff0000, v217
	v_lshlrev_b32_e32 v16, 16, v218
	v_and_b32_e32 v17, 0xffff0000, v218
	v_lshlrev_b32_e32 v20, 16, v219
	v_and_b32_e32 v21, 0xffff0000, v219
	s_waitcnt vmcnt(3)
	v_lshlrev_b32_e32 v22, 16, v220
	v_and_b32_e32 v23, 0xffff0000, v220
	v_lshlrev_b32_e32 v8, 16, v221
	v_and_b32_e32 v9, 0xffff0000, v221
	v_lshlrev_b32_e32 v24, 16, v222
	v_and_b32_e32 v25, 0xffff0000, v222
	v_lshlrev_b32_e32 v10, 16, v223
	v_and_b32_e32 v11, 0xffff0000, v223
	v_pk_fma_f32 v[6:7], v[6:7], v[14:15], v[8:9]
	v_pk_fma_f32 v[4:5], v[4:5], v[12:13], v[22:23]
	v_pk_fma_f32 v[8:9], v[2:3], v[20:21], v[10:11]
	v_pk_fma_f32 v[2:3], v[0:1], v[16:17], v[24:25]
	v_cvt_pk_bf16_f32 v0, v4, v5
	v_cvt_pk_bf16_f32 v1, v6, v7
	v_cvt_pk_bf16_f32 v2, v2, v3
	v_cvt_pk_bf16_f32 v3, v8, v9
	global_store_dwordx4 v[18:19], v[0:3], off offset:256
	s_cbranch_vccnz .LBB0_643
	s_andn2_b64 vcc, exec, s[0:1]
	s_cbranch_vccnz .LBB0_642
	s_barrier
	s_branch .LBB0_642

.LBB0_727:
	v_lshl_add_u32 v144, s38, 8, v146
	v_lshl_or_b32 v142, s37, 8, v148
	v_ashrrev_i32_e32 v145, 31, v144
	v_ashrrev_i32_e32 v143, 31, v142
	v_lshlrev_b64 v[140:141], 10, v[144:145]
	v_lshl_add_u64 v[140:141], v[140:141], 0, v[142:143]
	v_lshlrev_b64 v[140:141], 2, v[140:141]
	v_lshl_add_u64 v[158:159], s[2:3], 0, v[140:141]
	s_mov_b32 s98, s2
	s_mov_b32 s99, s3
	global_load_dwordx4 v[178:181], v140, s[98:99] offset:16
	s_mov_b32 s98, s2
	s_mov_b32 s99, s3
	global_load_dwordx4 v[182:185], v140, s[98:99]
	s_mov_b32 s98, s2
	s_mov_b32 s99, s3
	global_load_dwordx4 v[186:189], v140, s[98:99] offset:528
	s_mov_b32 s98, s2
	s_mov_b32 s99, s3
	global_load_dwordx4 v[190:193], v140, s[98:99] offset:512
	s_add_u32 s98, s2, 0x10000
	s_addc_u32 s99, s3, 0
	global_load_dwordx4 v[208:211], v140, s[98:99] offset:16
	s_add_u32 s98, s2, 0x10000
	s_addc_u32 s99, s3, 0
	global_load_dwordx4 v[212:215], v140, s[98:99]
	s_add_u32 s98, s2, 0x10000
	s_addc_u32 s99, s3, 0
	global_load_dwordx4 v[216:219], v140, s[98:99] offset:528
	s_add_u32 s98, s2, 0x10000
	s_addc_u32 s99, s3, 0
	global_load_dwordx4 v[220:223], v140, s[98:99] offset:512
	s_add_u32 s98, s2, 0x20000
	s_addc_u32 s99, s3, 0
	global_load_dwordx4 v[224:227], v140, s[98:99] offset:16
	s_add_u32 s98, s2, 0x20000
	s_addc_u32 s99, s3, 0
	global_load_dwordx4 v[228:231], v140, s[98:99]
	s_add_u32 s98, s2, 0x20000
	s_addc_u32 s99, s3, 0
	global_load_dwordx4 v[236:239], v140, s[98:99] offset:528
	s_add_u32 s98, s2, 0x20000
	s_addc_u32 s99, s3, 0
	global_load_dwordx4 v[240:243], v140, s[98:99] offset:512
	s_mov_b64 s[18:19], 0x80000
	s_andn2_b64 vcc, exec, s[4:5]
	s_waitcnt vmcnt(10)
	v_pk_add_f32 v[122:123], v[122:123], v[180:181]
	v_pk_add_f32 v[126:127], v[126:127], v[184:185]
	v_pk_add_f32 v[124:125], v[124:125], v[182:183]
	v_lshl_add_u64 v[154:155], s[6:7], 0, v[140:141]
	v_pk_add_f32 v[120:121], v[120:121], v[178:179]
	global_store_dwordx4 v[154:155], v[124:127], off
	global_store_dwordx4 v[154:155], v[120:123], off offset:16
	s_nop 0
	s_waitcnt vmcnt(10)
	v_pk_add_f32 v[114:115], v[114:115], v[188:189]
	v_pk_add_f32 v[112:113], v[112:113], v[186:187]
	global_store_dwordx4 v[154:155], v[112:115], off offset:528
	s_waitcnt vmcnt(11)
	v_pk_add_f32 v[118:119], v[118:119], v[192:193]
	v_pk_add_f32 v[116:117], v[116:117], v[190:191]
	v_or_b32_e32 v112, 16, v144
	v_ashrrev_i32_e32 v113, 31, v112
	v_lshlrev_b64 v[112:113], 10, v[112:113]
	v_lshl_add_u64 v[112:113], v[112:113], 0, v[142:143]
	global_store_dwordx4 v[154:155], v[116:119], off offset:512
	v_lshlrev_b64 v[120:121], 2, v[112:113]
	v_lshl_add_u64 v[122:123], s[2:3], 0, v[120:121]
	s_waitcnt vmcnt(10)
	v_pk_add_f32 v[106:107], v[106:107], v[210:211]
	s_waitcnt vmcnt(10)
	v_pk_add_f32 v[110:111], v[110:111], v[214:215]
	v_pk_add_f32 v[108:109], v[108:109], v[212:213]
	v_lshl_add_u64 v[116:117], s[6:7], 0, v[120:121]
	v_pk_add_f32 v[104:105], v[104:105], v[208:209]
	global_store_dwordx4 v[116:117], v[108:111], off
	global_store_dwordx4 v[116:117], v[104:107], off offset:16
	s_nop 0
	s_waitcnt vmcnt(10)
	v_pk_add_f32 v[98:99], v[98:99], v[218:219]
	v_pk_add_f32 v[96:97], v[96:97], v[216:217]
	global_store_dwordx4 v[116:117], v[96:99], off offset:528
	s_waitcnt vmcnt(11)
	v_pk_add_f32 v[102:103], v[102:103], v[222:223]
	v_pk_add_f32 v[100:101], v[100:101], v[220:221]
	v_or_b32_e32 v96, 32, v144
	v_ashrrev_i32_e32 v97, 31, v96
	v_lshlrev_b64 v[96:97], 10, v[96:97]
	v_lshl_add_u64 v[96:97], v[96:97], 0, v[142:143]
	global_store_dwordx4 v[116:117], v[100:103], off offset:512
	v_lshlrev_b64 v[104:105], 2, v[96:97]
	v_lshl_add_u64 v[106:107], s[2:3], 0, v[104:105]
	s_waitcnt vmcnt(10)
	v_pk_add_f32 v[90:91], v[90:91], v[226:227]
	s_waitcnt vmcnt(10)
	v_pk_add_f32 v[94:95], v[94:95], v[230:231]
	v_pk_add_f32 v[92:93], v[92:93], v[228:229]
	v_lshl_add_u64 v[100:101], s[6:7], 0, v[104:105]
	v_pk_add_f32 v[88:89], v[88:89], v[224:225]
	global_store_dwordx4 v[100:101], v[92:95], off
	global_store_dwordx4 v[100:101], v[88:91], off offset:16
	s_nop 0
	s_waitcnt vmcnt(10)
	v_pk_add_f32 v[82:83], v[82:83], v[238:239]
	v_pk_add_f32 v[80:81], v[80:81], v[236:237]
	global_store_dwordx4 v[100:101], v[80:83], off offset:528
	s_waitcnt vmcnt(11)
	v_pk_add_f32 v[86:87], v[86:87], v[242:243]
	v_pk_add_f32 v[84:85], v[84:85], v[240:241]
	v_or_b32_e32 v80, 48, v144
	v_ashrrev_i32_e32 v81, 31, v80
	v_lshlrev_b64 v[80:81], 10, v[80:81]
	v_lshl_add_u64 v[80:81], v[80:81], 0, v[142:143]
	global_store_dwordx4 v[100:101], v[84:87], off offset:512
	v_lshlrev_b64 v[88:89], 2, v[80:81]
	v_lshl_add_u64 v[90:91], s[2:3], 0, v[88:89]
	s_add_u32 s98, s2, 0x30000
	s_addc_u32 s99, s3, 0
	global_load_dwordx4 v[178:181], v140, s[98:99] offset:16
	s_add_u32 s98, s2, 0x30000
	s_addc_u32 s99, s3, 0
	global_load_dwordx4 v[182:185], v140, s[98:99]
	s_add_u32 s98, s2, 0x30000
	s_addc_u32 s99, s3, 0
	global_load_dwordx4 v[186:189], v140, s[98:99] offset:528
	s_add_u32 s98, s2, 0x30000
	s_addc_u32 s99, s3, 0
	global_load_dwordx4 v[190:193], v140, s[98:99] offset:512
	s_add_u32 s98, s2, 0x80000
	s_addc_u32 s99, s3, 0
	global_load_dwordx4 v[208:211], v140, s[98:99] offset:16
	s_add_u32 s98, s2, 0x80000
	s_addc_u32 s99, s3, 0
	global_load_dwordx4 v[212:215], v140, s[98:99]
	s_add_u32 s98, s2, 0x80000
	s_addc_u32 s99, s3, 0
	global_load_dwordx4 v[216:219], v140, s[98:99] offset:528
	s_add_u32 s98, s2, 0x80000
	s_addc_u32 s99, s3, 0
	global_load_dwordx4 v[220:223], v140, s[98:99] offset:512
	s_add_u32 s98, s2, 0x90000
	s_addc_u32 s99, s3, 0
	global_load_dwordx4 v[224:227], v140, s[98:99] offset:16
	s_add_u32 s98, s2, 0x90000
	s_addc_u32 s99, s3, 0
	global_load_dwordx4 v[228:231], v140, s[98:99]
	s_add_u32 s98, s2, 0x90000
	s_addc_u32 s99, s3, 0
	global_load_dwordx4 v[236:239], v140, s[98:99] offset:528
	s_add_u32 s98, s2, 0x90000
	s_addc_u32 s99, s3, 0
	global_load_dwordx4 v[240:243], v140, s[98:99] offset:512
	s_waitcnt vmcnt(10)
	v_pk_add_f32 v[74:75], v[74:75], v[180:181]
	s_waitcnt vmcnt(10)
	v_pk_add_f32 v[78:79], v[78:79], v[184:185]
	v_pk_add_f32 v[76:77], v[76:77], v[182:183]
	v_lshl_add_u64 v[84:85], s[6:7], 0, v[88:89]
	v_pk_add_f32 v[72:73], v[72:73], v[178:179]
	global_store_dwordx4 v[84:85], v[76:79], off
	global_store_dwordx4 v[84:85], v[72:75], off offset:16
	s_nop 0
	s_waitcnt vmcnt(10)
	v_pk_add_f32 v[66:67], v[66:67], v[188:189]
	s_waitcnt vmcnt(10)
	v_pk_add_f32 v[70:71], v[70:71], v[192:193]
	v_pk_add_f32 v[68:69], v[68:69], v[190:191]
	v_pk_add_f32 v[64:65], v[64:65], v[186:187]
	global_store_dwordx4 v[84:85], v[68:71], off offset:512
	global_store_dwordx4 v[84:85], v[64:67], off offset:528
	v_lshl_add_u64 v[72:73], v[140:141], 0, s[18:19]
	v_lshl_add_u64 v[74:75], s[2:3], 0, v[72:73]
	s_mov_b64 s[18:19], 0x90000
	s_waitcnt vmcnt(10)
	v_pk_add_f32 v[58:59], v[58:59], v[210:211]
	s_waitcnt vmcnt(10)
	v_pk_add_f32 v[62:63], v[62:63], v[214:215]
	v_pk_add_f32 v[60:61], v[60:61], v[212:213]
	v_lshl_add_u64 v[68:69], s[6:7], 0, v[72:73]
	v_pk_add_f32 v[56:57], v[56:57], v[208:209]
	global_store_dwordx4 v[68:69], v[60:63], off
	global_store_dwordx4 v[68:69], v[56:59], off offset:16
	s_nop 0
	s_waitcnt vmcnt(10)
	v_pk_add_f32 v[50:51], v[50:51], v[218:219]
	s_waitcnt vmcnt(10)
	v_pk_add_f32 v[54:55], v[54:55], v[222:223]
	v_pk_add_f32 v[52:53], v[52:53], v[220:221]
	v_pk_add_f32 v[48:49], v[48:49], v[216:217]
	global_store_dwordx4 v[68:69], v[52:55], off offset:512
	global_store_dwordx4 v[68:69], v[48:51], off offset:528
	v_lshl_add_u64 v[56:57], v[140:141], 0, s[18:19]
	v_lshl_add_u64 v[58:59], s[2:3], 0, v[56:57]
	s_mov_b64 s[18:19], 0xa0000
	s_waitcnt vmcnt(10)
	v_pk_add_f32 v[42:43], v[42:43], v[226:227]
	s_waitcnt vmcnt(10)
	v_pk_add_f32 v[46:47], v[46:47], v[230:231]
	v_pk_add_f32 v[44:45], v[44:45], v[228:229]
	v_lshl_add_u64 v[52:53], s[6:7], 0, v[56:57]
	v_pk_add_f32 v[40:41], v[40:41], v[224:225]
	global_store_dwordx4 v[52:53], v[44:47], off
	global_store_dwordx4 v[52:53], v[40:43], off offset:16
	s_nop 0
	s_waitcnt vmcnt(10)
	v_pk_add_f32 v[34:35], v[34:35], v[238:239]
	s_waitcnt vmcnt(10)
	v_pk_add_f32 v[38:39], v[38:39], v[242:243]
	v_pk_add_f32 v[36:37], v[36:37], v[240:241]
	v_pk_add_f32 v[32:33], v[32:33], v[236:237]
	global_store_dwordx4 v[52:53], v[36:39], off offset:512
	global_store_dwordx4 v[52:53], v[32:35], off offset:528
	v_lshl_add_u64 v[40:41], v[140:141], 0, s[18:19]
	v_lshl_add_u64 v[42:43], s[2:3], 0, v[40:41]
	s_add_u32 s98, s2, 0xa0000
	s_addc_u32 s99, s3, 0
	global_load_dwordx4 v[178:181], v140, s[98:99] offset:16
	s_add_u32 s98, s2, 0xa0000
	s_addc_u32 s99, s3, 0
	global_load_dwordx4 v[182:185], v140, s[98:99]
	s_add_u32 s98, s2, 0xa0000
	s_addc_u32 s99, s3, 0
	global_load_dwordx4 v[186:189], v140, s[98:99] offset:528
	s_add_u32 s98, s2, 0xa0000
	s_addc_u32 s99, s3, 0
	global_load_dwordx4 v[190:193], v140, s[98:99] offset:512
	s_add_u32 s98, s2, 0xb0000
	s_addc_u32 s99, s3, 0
	global_load_dwordx4 v[208:211], v140, s[98:99] offset:16
	s_add_u32 s98, s2, 0xb0000
	s_addc_u32 s99, s3, 0
	global_load_dwordx4 v[212:215], v140, s[98:99]
	s_add_u32 s98, s2, 0xb0000
	s_addc_u32 s99, s3, 0
	global_load_dwordx4 v[216:219], v140, s[98:99] offset:528
	s_add_u32 s98, s2, 0xb0000
	s_addc_u32 s99, s3, 0
	global_load_dwordx4 v[220:223], v140, s[98:99] offset:512
	s_mov_b64 s[18:19], 0xb0000
	s_waitcnt vmcnt(6)
	v_pk_add_f32 v[26:27], v[26:27], v[180:181]
	s_waitcnt vmcnt(6)
	v_pk_add_f32 v[30:31], v[30:31], v[184:185]
	v_pk_add_f32 v[28:29], v[28:29], v[182:183]
	v_lshl_add_u64 v[36:37], s[6:7], 0, v[40:41]
	v_pk_add_f32 v[24:25], v[24:25], v[178:179]
	global_store_dwordx4 v[36:37], v[28:31], off
	global_store_dwordx4 v[36:37], v[24:27], off offset:16
	s_nop 0
	s_waitcnt vmcnt(6)
	v_pk_add_f32 v[18:19], v[18:19], v[188:189]
	s_waitcnt vmcnt(6)
	v_pk_add_f32 v[22:23], v[22:23], v[192:193]
	v_pk_add_f32 v[20:21], v[20:21], v[190:191]
	v_pk_add_f32 v[16:17], v[16:17], v[186:187]
	global_store_dwordx4 v[36:37], v[20:23], off offset:512
	global_store_dwordx4 v[36:37], v[16:19], off offset:528
	v_lshl_add_u64 v[24:25], v[140:141], 0, s[18:19]
	v_lshl_add_u64 v[26:27], s[2:3], 0, v[24:25]
	s_mov_b64 s[18:19], -1
	s_waitcnt vmcnt(6)
	v_pk_add_f32 v[10:11], v[10:11], v[210:211]
	s_waitcnt vmcnt(6)
	v_pk_add_f32 v[14:15], v[14:15], v[214:215]
	v_pk_add_f32 v[12:13], v[12:13], v[212:213]
	v_lshl_add_u64 v[20:21], s[6:7], 0, v[24:25]
	v_pk_add_f32 v[8:9], v[8:9], v[208:209]
	global_store_dwordx4 v[20:21], v[12:15], off
	global_store_dwordx4 v[20:21], v[8:11], off offset:16
	s_nop 0
	s_waitcnt vmcnt(6)
	v_pk_add_f32 v[2:3], v[2:3], v[218:219]
	s_waitcnt vmcnt(6)
	v_pk_add_f32 v[6:7], v[6:7], v[222:223]
	v_pk_add_f32 v[4:5], v[4:5], v[220:221]
	v_pk_add_f32 v[0:1], v[0:1], v[216:217]
	global_store_dwordx4 v[20:21], v[4:7], off offset:512
	global_store_dwordx4 v[20:21], v[0:3], off offset:528
	s_cbranch_vccnz .LBB0_716
	s_andn2_b64 vcc, exec, s[0:1]
	s_cbranch_vccnz .LBB0_715
	s_barrier
	s_branch .LBB0_715
